# attention QK: K fragments prefetched 4 deep with counted lgkmcnt; next-tile LDS-DMA pieces interleaved between QK MFMAs
# speedup vs baseline: 1.0109x; 1.0109x over previous
; __device__ __forceinline__ int v_rd_base(int lane) { return ((lane & 3) << 3) | (((lane >> 2) & 3) << 6) | (((lane >> 4) & 1) << 5) | (((lane >> 5) & 1) << 8); }
; #define DMA_TILE(t, buf) do { const char* kt = (const char*)Kh + (size_t)(t) * (64 * 2048 * 2); const char* vt = (const char*)Vh + (size_t)(t) * (64 * 2048 * 2); \
;     _Pragma("unroll") for (int i = 0; i < 8; ++i) __builtin_amdgcn_global_load_lds((const unsigned*)((wid < 4 ? kt : vt) + src_off(wid * 8 + i, lane)), (LAS unsigned*)(lds + (buf) * 65536 + (wid * 8 + i) * 1024), 16, 0, 0); } while (0)
; __device__ __forceinline__ void dattn_unit(const bf16* __restrict__ Qb, const bf16* __restrict__ Kh, const bf16* __restrict__ Vh, int nq, int kv_lo, int kv_hi, int NT, ...
;     ...
;   DMA_TILE(0, 0);
;   for (int t = 0; t < NT; ++t) {
;     asm volatile("s_waitcnt vmcnt(0)" ::: "memory");
;     __builtin_amdgcn_s_barrier();
;     if (t + 1 < NT) DMA_TILE(t + 1, (t + 1) & 1);
;     const int rem = kvalid - 64 * t;
;     if (active && rem > 0) {
;       const bf16* Ks = (const bf16*)(lds + (t & 1) * 65536 + br * 16384);
;       const int vb = (int)(uintptr_t)(lds + (t & 1) * 65536 + 32768) + v_rd_base(lane);
;       f32x16 p0, p1; float mn, al; bf16x8 pa0, pa1, pa2, pa3;
;       p0 = f32x16{}; p1 = f32x16{};
; #pragma unroll
;       for (int d0 = 0; d0 < 8; ++d0) { const int cb = (d0 * 16 + hi * 8) * 2;
;         const bf16x8 b0 = *reinterpret_cast<const bf16x8*>((const char*)Ks + KSWZ(r32, cb));
;         const bf16x8 b1 = *reinterpret_cast<const bf16x8*>((const char*)Ks + KSWZ(32 + r32, cb));
;         p0 = __builtin_amdgcn_mfma_f32_32x32x16_bf16(b0, qr[d0], p0, 0, 0, 0);
;         p1 = __builtin_amdgcn_mfma_f32_32x32x16_bf16(b1, qr[d0], p1, 0, 0, 0);
;         }
.LBB0_939:
	s_waitcnt vmcnt(0)
	s_add_i32 s28, s28, 1
	s_barrier
	s_cmp_gt_i32 s25, 0
	s_cselect_b64 s[4:5], -1, 0
	s_and_b64 s[4:5], s[12:13], s[4:5]
	s_cbranch_scc0 .Latt_nocompute
	s_cmp_ge_u32 s28, s23
	s_cbranch_scc1 .Latt_qk_nodma
	s_and_b32 s4, s27, 0x10000
	s_add_i32 s29, s4, 0
	s_add_i32 s4, s29, s26
	s_add_i32 s32, s27, 0x10000
	s_and_b32 s32, s32, 0x10000
	s_add_i32 s32, s24, s32
	v_add3_u32 v0, s4, v238, v236
	ds_read_b128 v[194:197], v0
	ds_read_b128 v[198:201], v0 offset:8192
	v_add3_u32 v0, s4, v239, v236
	ds_read_b128 v[202:205], v0
	ds_read_b128 v[206:209], v0 offset:8192
	v_add3_u32 v0, s4, v240, v236
	s_waitcnt lgkmcnt(3)
	v_mfma_f32_32x32x16_bf16 v[146:161], v[194:197], v[162:165], 0
	ds_read_b128 v[194:197], v0
	v_lshl_add_u64 v[250:251], s[14:15], 0, v[212:213]
	s_mov_b32 m0, s32
	s_nop 0
	global_load_lds_dwordx4 v[250:251], off
	s_waitcnt lgkmcnt(3)
	v_mfma_f32_32x32x16_bf16 v[130:145], v[198:201], v[162:165], 0
	ds_read_b128 v[198:201], v0 offset:8192
	v_lshl_add_u64 v[250:251], s[14:15], 0, v[214:215]
	s_add_i32 m0, s32, 0x400
	s_nop 0
	global_load_lds_dwordx4 v[250:251], off
	v_add3_u32 v0, s4, v241, v236
	s_waitcnt lgkmcnt(3)
	v_mfma_f32_32x32x16_bf16 v[146:161], v[202:205], v[166:169], v[146:161]
	ds_read_b128 v[202:205], v0
	v_lshl_add_u64 v[250:251], s[14:15], 0, v[216:217]
	s_add_i32 m0, s32, 0x800
	s_nop 0
	global_load_lds_dwordx4 v[250:251], off
	s_waitcnt lgkmcnt(3)
	v_mfma_f32_32x32x16_bf16 v[130:145], v[206:209], v[166:169], v[130:145]
	ds_read_b128 v[206:209], v0 offset:8192
	v_lshl_add_u64 v[250:251], s[14:15], 0, v[218:219]
	s_add_i32 m0, s32, 0xc00
	s_nop 0
	global_load_lds_dwordx4 v[250:251], off
	v_add3_u32 v0, s4, v242, v236
	s_waitcnt lgkmcnt(3)
	v_mfma_f32_32x32x16_bf16 v[146:161], v[194:197], v[170:173], v[146:161]
	ds_read_b128 v[194:197], v0
	v_lshl_add_u64 v[250:251], s[14:15], 0, v[220:221]
	s_add_i32 m0, s32, 0x1000
	s_nop 0
	global_load_lds_dwordx4 v[250:251], off
	s_waitcnt lgkmcnt(3)
	v_mfma_f32_32x32x16_bf16 v[130:145], v[198:201], v[170:173], v[130:145]
	ds_read_b128 v[198:201], v0 offset:8192
	v_lshl_add_u64 v[250:251], s[14:15], 0, v[222:223]
	s_add_i32 m0, s32, 0x1400
	s_nop 0
	global_load_lds_dwordx4 v[250:251], off
	v_add3_u32 v0, s4, v243, v236
	s_waitcnt lgkmcnt(3)
	v_mfma_f32_32x32x16_bf16 v[146:161], v[202:205], v[174:177], v[146:161]
	ds_read_b128 v[202:205], v0
	v_lshl_add_u64 v[250:251], s[14:15], 0, v[224:225]
	s_add_i32 m0, s32, 0x1800
	s_nop 0
	global_load_lds_dwordx4 v[250:251], off
	s_waitcnt lgkmcnt(3)
	v_mfma_f32_32x32x16_bf16 v[130:145], v[206:209], v[174:177], v[130:145]
	ds_read_b128 v[206:209], v0 offset:8192
	v_lshl_add_u64 v[250:251], s[14:15], 0, v[226:227]
	s_add_i32 m0, s32, 0x1c00
	s_nop 0
	global_load_lds_dwordx4 v[250:251], off
	v_add3_u32 v0, s4, v244, v236
	s_waitcnt lgkmcnt(3)
	v_mfma_f32_32x32x16_bf16 v[146:161], v[194:197], v[178:181], v[146:161]
	ds_read_b128 v[194:197], v0
	s_waitcnt lgkmcnt(3)
	v_mfma_f32_32x32x16_bf16 v[130:145], v[198:201], v[178:181], v[130:145]
	ds_read_b128 v[198:201], v0 offset:8192
	v_add3_u32 v0, s4, v245, v236
	s_waitcnt lgkmcnt(3)
	v_mfma_f32_32x32x16_bf16 v[146:161], v[202:205], v[182:185], v[146:161]
	ds_read_b128 v[202:205], v0
	s_waitcnt lgkmcnt(3)
	v_mfma_f32_32x32x16_bf16 v[130:145], v[206:209], v[182:185], v[130:145]
	ds_read_b128 v[206:209], v0 offset:8192
	s_waitcnt lgkmcnt(3)
	v_mfma_f32_32x32x16_bf16 v[146:161], v[194:197], v[186:189], v[146:161]
	s_waitcnt lgkmcnt(2)
	v_mfma_f32_32x32x16_bf16 v[130:145], v[198:201], v[186:189], v[130:145]
	s_waitcnt lgkmcnt(1)
	v_mfma_f32_32x32x16_bf16 v[146:161], v[202:205], v[190:193], v[146:161]
	s_waitcnt lgkmcnt(0)
	v_mfma_f32_32x32x16_bf16 v[130:145], v[206:209], v[190:193], v[130:145]
	s_branch .Latt_qk_done
; __device__ __forceinline__ void partialSM(f32x16& p0, f32x16& p1, float& m_reg, float& mn, float& alpha, int rem, int hi) {
;     ...
;   if (rem < 64) {
; #pragma unroll
;     for (int r = 0; r < 16; ++r) { if (8 * (r >> 2) >= rem) p0[r] = -1e30f; if (32 + 8 * (r >> 2) >= rem) p1[r] = -1e30f; }
; __device__ __forceinline__ void dattn_unit(const bf16* __restrict__ Qb, const bf16* __restrict__ Kh, const bf16* __restrict__ Vh, int nq, int kv_lo, int kv_hi, int NT, ...
;     ...
;       for (int d0 = 0; d0 < 8; ++d0) { const int cb = (d0 * 16 + hi * 8) * 2;
;         const bf16x8 b0 = *reinterpret_cast<const bf16x8*>((const char*)Ks + KSWZ(r32, cb));
;         const bf16x8 b1 = *reinterpret_cast<const bf16x8*>((const char*)Ks + KSWZ(32 + r32, cb));
;         p0 = __builtin_amdgcn_mfma_f32_32x32x16_bf16(b0, qr[d0], p0, 0, 0, 0);
;         p1 = __builtin_amdgcn_mfma_f32_32x32x16_bf16(b1, qr[d0], p1, 0, 0, 0);
;         }
;       partialSM(p0, p1, m_reg, mn, al, rem, hi);
.Latt_qk_nodma:
	s_and_b32 s4, s27, 0x10000
	s_add_i32 s29, s4, 0
	s_add_i32 s4, s29, s26
	v_add3_u32 v0, s4, v238, v236
	ds_read_b128 v[194:197], v0
	ds_read_b128 v[198:201], v0 offset:8192
	v_add3_u32 v0, s4, v239, v236
	ds_read_b128 v[202:205], v0
	ds_read_b128 v[206:209], v0 offset:8192
	v_add3_u32 v0, s4, v240, v236
	s_waitcnt lgkmcnt(3)
	v_mfma_f32_32x32x16_bf16 v[146:161], v[194:197], v[162:165], 0
	ds_read_b128 v[194:197], v0
	s_waitcnt lgkmcnt(3)
	v_mfma_f32_32x32x16_bf16 v[130:145], v[198:201], v[162:165], 0
	ds_read_b128 v[198:201], v0 offset:8192
	v_add3_u32 v0, s4, v241, v236
	s_waitcnt lgkmcnt(3)
	v_mfma_f32_32x32x16_bf16 v[146:161], v[202:205], v[166:169], v[146:161]
	ds_read_b128 v[202:205], v0
	s_waitcnt lgkmcnt(3)
	v_mfma_f32_32x32x16_bf16 v[130:145], v[206:209], v[166:169], v[130:145]
	ds_read_b128 v[206:209], v0 offset:8192
	v_add3_u32 v0, s4, v242, v236
	s_waitcnt lgkmcnt(3)
	v_mfma_f32_32x32x16_bf16 v[146:161], v[194:197], v[170:173], v[146:161]
	ds_read_b128 v[194:197], v0
	s_waitcnt lgkmcnt(3)
	v_mfma_f32_32x32x16_bf16 v[130:145], v[198:201], v[170:173], v[130:145]
	ds_read_b128 v[198:201], v0 offset:8192
	v_add3_u32 v0, s4, v243, v236
	s_waitcnt lgkmcnt(3)
	v_mfma_f32_32x32x16_bf16 v[146:161], v[202:205], v[174:177], v[146:161]
	ds_read_b128 v[202:205], v0
	s_waitcnt lgkmcnt(3)
	v_mfma_f32_32x32x16_bf16 v[130:145], v[206:209], v[174:177], v[130:145]
	ds_read_b128 v[206:209], v0 offset:8192
	v_add3_u32 v0, s4, v244, v236
	s_waitcnt lgkmcnt(3)
	v_mfma_f32_32x32x16_bf16 v[146:161], v[194:197], v[178:181], v[146:161]
	ds_read_b128 v[194:197], v0
	s_waitcnt lgkmcnt(3)
	v_mfma_f32_32x32x16_bf16 v[130:145], v[198:201], v[178:181], v[130:145]
	ds_read_b128 v[198:201], v0 offset:8192
	v_add3_u32 v0, s4, v245, v236
	s_waitcnt lgkmcnt(3)
	v_mfma_f32_32x32x16_bf16 v[146:161], v[202:205], v[182:185], v[146:161]
	ds_read_b128 v[202:205], v0
	s_waitcnt lgkmcnt(3)
	v_mfma_f32_32x32x16_bf16 v[130:145], v[206:209], v[182:185], v[130:145]
	ds_read_b128 v[206:209], v0 offset:8192
	s_waitcnt lgkmcnt(3)
	v_mfma_f32_32x32x16_bf16 v[146:161], v[194:197], v[186:189], v[146:161]
	s_waitcnt lgkmcnt(2)
	v_mfma_f32_32x32x16_bf16 v[130:145], v[198:201], v[186:189], v[130:145]
	s_waitcnt lgkmcnt(1)
	v_mfma_f32_32x32x16_bf16 v[146:161], v[202:205], v[190:193], v[146:161]
	s_waitcnt lgkmcnt(0)
	v_mfma_f32_32x32x16_bf16 v[130:145], v[206:209], v[190:193], v[130:145]
.Latt_qk_done:
	s_cmp_gt_u32 s25, 63
	s_cbranch_scc1 .LBB0_946
	s_cmp_gt_u32 s25, 8
	s_cselect_b64 s[16:17], -1, 0
	s_cmp_gt_u32 s25, 16
	s_cselect_b64 s[18:19], -1, 0
	s_cmp_gt_u32 s25, 24
	s_cselect_b64 vcc, -1, 0
	s_cmp_gt_u32 s25, 56
	s_cbranch_scc1 .LBB0_945
	s_cmp_gt_u32 s25, 48
	s_cselect_b64 s[4:5], -1, 0
	s_cmp_gt_u32 s25, 40
	s_cselect_b64 s[6:7], -1, 0
	s_cmp_gt_u32 s25, 32
	s_cselect_b64 s[8:9], -1, 0
	s_or_b64 s[6:7], s[4:5], s[6:7]
	s_or_b64 s[8:9], s[6:7], s[8:9]
	v_mov_b32_e32 v145, 0xf149f2ca
	s_or_b64 s[8:9], s[8:9], s[4:5]
	v_cndmask_b32_e64 v138, v145, v138, s[4:5]
	v_cndmask_b32_e64 v134, v145, v134, s[6:7]
	v_cndmask_b32_e64 v130, v145, v130, s[8:9]
	v_cndmask_b32_e64 v131, v145, v131, s[8:9]
	v_cndmask_b32_e64 v132, v145, v132, s[8:9]
	v_cndmask_b32_e64 v133, v145, v133, s[8:9]
	v_cndmask_b32_e64 v135, v145, v135, s[6:7]
	v_cndmask_b32_e64 v136, v145, v136, s[6:7]
	v_cndmask_b32_e64 v137, v145, v137, s[6:7]
	v_cndmask_b32_e64 v139, v145, v139, s[4:5]
	v_cndmask_b32_e64 v140, v145, v140, s[4:5]
	v_cndmask_b32_e64 v141, v145, v141, s[4:5]
	v_mov_b32_e32 v144, v145
	v_mov_b32_e32 v143, v145
	v_mov_b32_e32 v142, v145

; #define DMA_TILE(t, buf) do { const char* kt = (const char*)Kh + (size_t)(t) * (64 * 2048 * 2); const char* vt = (const char*)Vh + (size_t)(t) * (64 * 2048 * 2); \
;     _Pragma("unroll") for (int i = 0; i < 8; ++i) __builtin_amdgcn_global_load_lds((const unsigned*)((wid < 4 ? kt : vt) + src_off(wid * 8 + i, lane)), (LAS unsigned*)(lds + (buf) * 65536 + (wid * 8 + i) * 1024), 16, 0, 0); } while (0)
; __device__ __forceinline__ void dattn_unit(const bf16* __restrict__ Qb, const bf16* __restrict__ Kh, const bf16* __restrict__ Vh, int nq, int kv_lo, int kv_hi, int NT, ...
;     ...
;   DMA_TILE(0, 0);
;   for (int t = 0; t < NT; ++t) {
;     asm volatile("s_waitcnt vmcnt(0)" ::: "memory");
;     __builtin_amdgcn_s_barrier();
;     if (t + 1 < NT) DMA_TILE(t + 1, (t + 1) & 1);
.Latt_nocompute:
	s_cmp_ge_u32 s28, s23
	s_cbranch_scc1 .LBB0_938
	s_add_i32 s32, s27, 0x10000
	s_and_b32 s32, s32, 0x10000
	s_add_i32 s32, s24, s32
	v_lshl_add_u64 v[250:251], s[14:15], 0, v[212:213]
	s_mov_b32 m0, s32
	s_nop 0
	global_load_lds_dwordx4 v[250:251], off
	v_lshl_add_u64 v[250:251], s[14:15], 0, v[214:215]
	s_add_i32 m0, s32, 0x400
	s_nop 0
	global_load_lds_dwordx4 v[250:251], off
	v_lshl_add_u64 v[250:251], s[14:15], 0, v[216:217]
	s_add_i32 m0, s32, 0x800
	s_nop 0
	global_load_lds_dwordx4 v[250:251], off
	v_lshl_add_u64 v[250:251], s[14:15], 0, v[218:219]
	s_add_i32 m0, s32, 0xc00
	s_nop 0
	global_load_lds_dwordx4 v[250:251], off
	v_lshl_add_u64 v[250:251], s[14:15], 0, v[220:221]
	s_add_i32 m0, s32, 0x1000
	s_nop 0
	global_load_lds_dwordx4 v[250:251], off
	v_lshl_add_u64 v[250:251], s[14:15], 0, v[222:223]
	s_add_i32 m0, s32, 0x1400
	s_nop 0
	global_load_lds_dwordx4 v[250:251], off
	v_lshl_add_u64 v[250:251], s[14:15], 0, v[224:225]
	s_add_i32 m0, s32, 0x1800
	s_nop 0
	global_load_lds_dwordx4 v[250:251], off
	v_lshl_add_u64 v[250:251], s[14:15], 0, v[226:227]
	s_add_i32 m0, s32, 0x1c00
	s_nop 0
	global_load_lds_dwordx4 v[250:251], off
	s_branch .LBB0_938
